# v25 plus: F1 epilogue store addresses advance a running 64-bit pointer per row group instead of eight 64-bit multiply-adds
# speedup vs baseline: 1.0118x; 1.0002x over previous
.LBB0_577:
	ds_read2_b32 v[150:151], v146 offset1:16
	v_pk_mul_f32 v[120:121], v[124:125], v[120:121]
	v_pk_mul_f32 v[112:113], v[116:117], v[112:113]
	v_pk_mul_f32 v[114:115], v[118:119], v[114:115]
	v_pk_mul_f32 v[122:123], v[126:127], v[122:123]
	s_waitcnt lgkmcnt(0)
	v_mul_f32_e32 v149, 0xbfb8aa3b, v150
	v_mul_f32_e32 v152, v150, v150
	v_mul_f32_e32 v150, v124, v149
	v_mul_f32_e32 v153, v116, v149
	v_exp_f32_e32 v150, v150
	v_mul_f32_e32 v154, v125, v149
	v_exp_f32_e32 v153, v153
	v_exp_f32_e32 v155, v154
	v_add_f32_e32 v150, 1.0, v150
	v_rcp_f32_e32 v154, v150
	v_add_f32_e32 v150, 1.0, v153
	v_add_f32_e32 v153, 1.0, v155
	v_rcp_f32_e32 v156, v150
	v_mul_f32_e32 v150, v117, v149
	v_rcp_f32_e32 v155, v153
	v_exp_f32_e32 v150, v150
	v_mul_f32_e32 v116, v126, v149
	v_mul_f32_e32 v119, v119, v149
	v_pk_mul_f32 v[124:125], v[152:153], v[154:155] op_sel_hi:[0,1]
	v_pk_mul_f32 v[120:121], v[120:121], v[124:125]
	v_add_f32_e32 v124, 1.0, v150
	v_rcp_f32_e32 v157, v124
	v_exp_f32_e32 v124, v116
	v_mul_f32_e32 v116, v118, v149
	v_exp_f32_e32 v125, v116
	v_exp_f32_e32 v126, v119
	v_add_f32_e32 v118, 1.0, v124
	v_rcp_f32_e32 v118, v118
	v_add_f32_e32 v124, 1.0, v125
	v_mul_f32_e32 v125, v127, v149
	v_exp_f32_e32 v125, v125
	v_rcp_f32_e32 v124, v124
	v_pk_mul_f32 v[116:117], v[152:153], v[156:157] op_sel_hi:[0,1]
	v_pk_mul_f32 v[116:117], v[112:113], v[116:117]
	v_add_f32_e32 v119, 1.0, v125
	v_rcp_f32_e32 v119, v119
	v_add_f32_e32 v125, 1.0, v126
	v_rcp_f32_e32 v125, v125
	v_lshl_add_u32 v148, s42, 8, v142
	v_pk_mul_f32 v[112:113], v[152:153], v[118:119] op_sel_hi:[0,1]
	v_pk_mul_f32 v[118:119], v[122:123], v[112:113]
	v_pk_mul_f32 v[112:113], v[152:153], v[124:125] op_sel_hi:[0,1]
	v_pk_mul_f32 v[122:123], v[114:115], v[112:113]
	v_mov_b64_e32 v[112:113], s[48:49]
	v_mad_i64_i32 v[114:115], s[18:19], v148, s75, v[112:113]
	s_lshl_b32 s18, s37, 7
	s_ashr_i32 s19, s18, 31
	s_lshl_b64 s[18:19], s[18:19], 1
	v_lshl_add_u64 v[114:115], v[114:115], 0, s[18:19]
	v_lshl_add_u64 v[124:125], v[114:115], 0, v[176:177]
	v_mov_b32_e32 v210, v124
	v_mov_b32_e32 v211, v125
	v_cvt_pk_f16_f32 v114, v120, v121
	v_cvt_pk_f16_f32 v115, v118, v119
	v_cvt_pk_f16_f32 v116, v116, v117
	v_cvt_pk_f16_f32 v117, v122, v123
	v_mul_f32_e32 v120, 0xbfb8aa3b, v151
	ds_read2_b32 v[140:141], v146 offset0:32 offset1:48
	flat_store_dwordx4 v[124:125], v[114:117]
	v_mul_f32_e32 v118, v109, v120
	v_exp_f32_e32 v119, v118
	v_mul_f32_e32 v117, v100, v120
	v_mul_f32_e32 v114, v108, v120
	v_exp_f32_e32 v117, v117
	v_exp_f32_e32 v116, v114
	v_mul_f32_e32 v121, v101, v120
	v_add_f32_e32 v117, 1.0, v117
	v_add_f32_e32 v116, 1.0, v116
	v_rcp_f32_e32 v118, v117
	v_add_f32_e32 v117, 1.0, v119
	v_rcp_f32_e32 v116, v116
	v_rcp_f32_e32 v117, v117
	v_exp_f32_e32 v119, v121
	v_mul_f32_e32 v114, v151, v151
	v_pk_mul_f32 v[104:105], v[108:109], v[104:105]
	v_pk_mul_f32 v[108:109], v[114:115], v[116:117] op_sel_hi:[0,1]
	v_pk_mul_f32 v[104:105], v[104:105], v[108:109]
	v_add_f32_e32 v108, 1.0, v119
	v_pk_mul_f32 v[96:97], v[100:101], v[96:97]
	v_mul_f32_e32 v100, v110, v120
	v_rcp_f32_e32 v119, v108
	v_exp_f32_e32 v108, v100
	v_mul_f32_e32 v100, v102, v120
	v_exp_f32_e32 v109, v100
	v_pk_mul_f32 v[98:99], v[102:103], v[98:99]
	v_add_f32_e32 v102, 1.0, v108
	v_mul_f32_e32 v103, v103, v120
	v_add_f32_e32 v108, 1.0, v109
	v_mul_f32_e32 v109, v111, v120
	v_exp_f32_e32 v109, v109
	v_pk_mul_f32 v[106:107], v[110:111], v[106:107]
	v_exp_f32_e32 v110, v103
	v_rcp_f32_e32 v102, v102
	v_add_f32_e32 v103, 1.0, v109
	v_rcp_f32_e32 v103, v103
	v_add_f32_e32 v109, 1.0, v110
	v_rcp_f32_e32 v108, v108
	v_rcp_f32_e32 v109, v109
	v_pk_mul_f32 v[100:101], v[114:115], v[118:119] op_sel_hi:[0,1]
	v_pk_mul_f32 v[100:101], v[96:97], v[100:101]
	v_pk_mul_f32 v[96:97], v[114:115], v[102:103] op_sel_hi:[0,1]
	v_pk_mul_f32 v[102:103], v[106:107], v[96:97]
	v_pk_mul_f32 v[96:97], v[114:115], v[108:109] op_sel_hi:[0,1]
	v_pk_mul_f32 v[106:107], v[98:99], v[96:97]
	v_cvt_pk_f16_f32 v96, v104, v105
	v_cvt_pk_f16_f32 v97, v102, v103
	v_cvt_pk_f16_f32 v98, v100, v101
	v_cvt_pk_f16_f32 v99, v106, v107
	s_waitcnt lgkmcnt(0)
	v_mul_f32_e32 v102, 0xbfb8aa3b, v140
	v_add_co_u32_e32 v210, vcc, 0x16000, v210
	v_addc_co_u32_e32 v211, vcc, 0, v211, vcc
	flat_store_dwordx4 v[210:211], v[96:99]
	v_mul_f32_e32 v100, v93, v102
	v_exp_f32_e32 v101, v100
	v_mul_f32_e32 v99, v84, v102
	v_mul_f32_e32 v96, v92, v102
	v_exp_f32_e32 v99, v99
	v_exp_f32_e32 v98, v96
	v_mul_f32_e32 v103, v85, v102
	v_add_f32_e32 v99, 1.0, v99
	v_add_f32_e32 v98, 1.0, v98
	v_rcp_f32_e32 v100, v99
	v_add_f32_e32 v99, 1.0, v101
	v_rcp_f32_e32 v98, v98
	v_rcp_f32_e32 v99, v99
	v_exp_f32_e32 v101, v103
	v_mul_f32_e32 v96, v140, v140
	v_pk_mul_f32 v[88:89], v[92:93], v[88:89]
	v_pk_mul_f32 v[92:93], v[96:97], v[98:99] op_sel_hi:[0,1]
	v_pk_mul_f32 v[88:89], v[88:89], v[92:93]
	v_add_f32_e32 v92, 1.0, v101
	v_pk_mul_f32 v[80:81], v[84:85], v[80:81]
	v_mul_f32_e32 v84, v94, v102
	v_rcp_f32_e32 v101, v92
	v_exp_f32_e32 v92, v84
	v_mul_f32_e32 v84, v86, v102
	v_exp_f32_e32 v93, v84
	v_pk_mul_f32 v[82:83], v[86:87], v[82:83]
	v_add_f32_e32 v86, 1.0, v92
	v_mul_f32_e32 v87, v87, v102
	v_add_f32_e32 v92, 1.0, v93
	v_mul_f32_e32 v93, v95, v102
	v_exp_f32_e32 v93, v93
	v_pk_mul_f32 v[90:91], v[94:95], v[90:91]
	v_exp_f32_e32 v94, v87
	v_rcp_f32_e32 v86, v86
	v_add_f32_e32 v87, 1.0, v93
	v_rcp_f32_e32 v87, v87
	v_add_f32_e32 v93, 1.0, v94
	v_rcp_f32_e32 v92, v92
	v_rcp_f32_e32 v93, v93
	v_pk_mul_f32 v[84:85], v[96:97], v[100:101] op_sel_hi:[0,1]
	v_pk_mul_f32 v[84:85], v[80:81], v[84:85]
	v_pk_mul_f32 v[80:81], v[96:97], v[86:87] op_sel_hi:[0,1]
	v_pk_mul_f32 v[86:87], v[90:91], v[80:81]
	v_pk_mul_f32 v[80:81], v[96:97], v[92:93] op_sel_hi:[0,1]
	v_pk_mul_f32 v[90:91], v[82:83], v[80:81]
	v_cvt_pk_f16_f32 v80, v88, v89
	v_cvt_pk_f16_f32 v81, v86, v87
	v_cvt_pk_f16_f32 v82, v84, v85
	v_cvt_pk_f16_f32 v83, v90, v91
	v_mul_f32_e32 v86, 0xbfb8aa3b, v141
	v_add_co_u32_e32 v210, vcc, 0x16000, v210
	v_addc_co_u32_e32 v211, vcc, 0, v211, vcc
	flat_store_dwordx4 v[210:211], v[80:83]
	v_mul_f32_e32 v84, v77, v86
	v_exp_f32_e32 v85, v84
	v_mul_f32_e32 v83, v68, v86
	v_mul_f32_e32 v80, v76, v86
	v_exp_f32_e32 v83, v83
	v_exp_f32_e32 v82, v80
	v_mul_f32_e32 v87, v69, v86
	v_add_f32_e32 v83, 1.0, v83
	v_add_f32_e32 v82, 1.0, v82
	v_rcp_f32_e32 v84, v83
	v_add_f32_e32 v83, 1.0, v85
	v_rcp_f32_e32 v82, v82
	v_rcp_f32_e32 v83, v83
	v_exp_f32_e32 v85, v87
	v_mul_f32_e32 v80, v141, v141
	v_pk_mul_f32 v[72:73], v[76:77], v[72:73]
	v_pk_mul_f32 v[76:77], v[80:81], v[82:83] op_sel_hi:[0,1]
	v_pk_mul_f32 v[72:73], v[72:73], v[76:77]
	v_add_f32_e32 v76, 1.0, v85
	v_pk_mul_f32 v[64:65], v[68:69], v[64:65]
	v_mul_f32_e32 v68, v78, v86
	v_rcp_f32_e32 v85, v76
	v_exp_f32_e32 v76, v68
	v_mul_f32_e32 v68, v70, v86
	v_exp_f32_e32 v77, v68
	v_pk_mul_f32 v[66:67], v[70:71], v[66:67]
	v_add_f32_e32 v70, 1.0, v76
	v_mul_f32_e32 v71, v71, v86
	v_add_f32_e32 v76, 1.0, v77
	v_mul_f32_e32 v77, v79, v86
	v_exp_f32_e32 v77, v77
	v_pk_mul_f32 v[74:75], v[78:79], v[74:75]
	v_exp_f32_e32 v78, v71
	v_rcp_f32_e32 v70, v70
	v_add_f32_e32 v71, 1.0, v77
	v_rcp_f32_e32 v71, v71
	v_add_f32_e32 v77, 1.0, v78
	v_rcp_f32_e32 v76, v76
	v_rcp_f32_e32 v77, v77
	v_pk_mul_f32 v[68:69], v[80:81], v[84:85] op_sel_hi:[0,1]
	v_pk_mul_f32 v[68:69], v[64:65], v[68:69]
	v_pk_mul_f32 v[64:65], v[80:81], v[70:71] op_sel_hi:[0,1]
	v_pk_mul_f32 v[70:71], v[74:75], v[64:65]
	v_pk_mul_f32 v[64:65], v[80:81], v[76:77] op_sel_hi:[0,1]
	v_pk_mul_f32 v[74:75], v[66:67], v[64:65]
	v_cvt_pk_f16_f32 v64, v72, v73
	v_cvt_pk_f16_f32 v65, v70, v71
	v_cvt_pk_f16_f32 v66, v68, v69
	v_cvt_pk_f16_f32 v67, v74, v75
	v_add_co_u32_e32 v210, vcc, 0x16000, v210
	v_addc_co_u32_e32 v211, vcc, 0, v211, vcc
	flat_store_dwordx4 v[210:211], v[64:67]
	ds_read2_b32 v[66:67], v146 offset0:128 offset1:144
	ds_read2_b32 v[64:65], v146 offset0:160 offset1:176
	v_pk_mul_f32 v[56:57], v[60:61], v[56:57]
	v_pk_mul_f32 v[48:49], v[52:53], v[48:49]
	v_pk_mul_f32 v[50:51], v[54:55], v[50:51]
	s_waitcnt lgkmcnt(0)
	v_mul_f32_e32 v73, 0xbfb8aa3b, v66
	v_mul_f32_e32 v69, v52, v73
	v_mul_f32_e32 v68, v60, v73
	v_exp_f32_e32 v69, v69
	v_mul_f32_e32 v70, v61, v73
	v_exp_f32_e32 v68, v68
	v_exp_f32_e32 v71, v70
	v_add_f32_e32 v69, 1.0, v69
	v_rcp_f32_e32 v70, v69
	v_add_f32_e32 v68, 1.0, v68
	v_add_f32_e32 v69, 1.0, v71
	v_rcp_f32_e32 v68, v68
	v_mul_f32_e32 v74, v53, v73
	v_rcp_f32_e32 v69, v69
	v_exp_f32_e32 v71, v74
	v_mul_f32_e32 v66, v66, v66
	v_mul_f32_e32 v52, v62, v73
	v_pk_mul_f32 v[60:61], v[66:67], v[68:69] op_sel_hi:[0,1]
	v_pk_mul_f32 v[56:57], v[56:57], v[60:61]
	v_add_f32_e32 v60, 1.0, v71
	v_rcp_f32_e32 v71, v60
	v_exp_f32_e32 v60, v52
	v_mul_f32_e32 v52, v54, v73
	v_exp_f32_e32 v61, v52
	v_mul_f32_e32 v55, v55, v73
	v_add_f32_e32 v54, 1.0, v60
	v_pk_mul_f32 v[58:59], v[62:63], v[58:59]
	v_add_f32_e32 v60, 1.0, v61
	v_mul_f32_e32 v61, v63, v73
	v_exp_f32_e32 v61, v61
	v_exp_f32_e32 v62, v55
	v_rcp_f32_e32 v54, v54
	v_rcp_f32_e32 v60, v60
	v_add_f32_e32 v55, 1.0, v61
	v_rcp_f32_e32 v55, v55
	v_add_f32_e32 v61, 1.0, v62
	v_rcp_f32_e32 v61, v61
	v_pk_mul_f32 v[52:53], v[66:67], v[70:71] op_sel_hi:[0,1]
	v_pk_mul_f32 v[52:53], v[48:49], v[52:53]
	v_pk_mul_f32 v[48:49], v[66:67], v[54:55] op_sel_hi:[0,1]
	v_pk_mul_f32 v[54:55], v[58:59], v[48:49]
	v_pk_mul_f32 v[48:49], v[66:67], v[60:61] op_sel_hi:[0,1]
	v_pk_mul_f32 v[58:59], v[50:51], v[48:49]
	v_cvt_pk_f16_f32 v48, v56, v57
	v_cvt_pk_f16_f32 v49, v54, v55
	v_cvt_pk_f16_f32 v50, v52, v53
	v_cvt_pk_f16_f32 v51, v58, v59
	v_mul_f32_e32 v54, 0xbfb8aa3b, v67
	v_add_co_u32_e32 v210, vcc, 0x6e000, v210
	v_addc_co_u32_e32 v211, vcc, 0, v211, vcc
	flat_store_dwordx4 v[210:211], v[48:51]
	v_mul_f32_e32 v52, v45, v54
	v_exp_f32_e32 v53, v52
	v_mul_f32_e32 v51, v36, v54
	v_mul_f32_e32 v48, v44, v54
	v_exp_f32_e32 v51, v51
	v_exp_f32_e32 v50, v48
	v_mul_f32_e32 v55, v37, v54
	v_add_f32_e32 v51, 1.0, v51
	v_add_f32_e32 v50, 1.0, v50
	v_rcp_f32_e32 v52, v51
	v_add_f32_e32 v51, 1.0, v53
	v_rcp_f32_e32 v50, v50
	v_rcp_f32_e32 v51, v51
	v_exp_f32_e32 v53, v55
	v_mul_f32_e32 v48, v67, v67
	v_pk_mul_f32 v[40:41], v[44:45], v[40:41]
	v_pk_mul_f32 v[44:45], v[48:49], v[50:51] op_sel_hi:[0,1]
	v_pk_mul_f32 v[40:41], v[40:41], v[44:45]
	v_add_f32_e32 v44, 1.0, v53
	v_pk_mul_f32 v[32:33], v[36:37], v[32:33]
	v_mul_f32_e32 v36, v46, v54
	v_rcp_f32_e32 v53, v44
	v_exp_f32_e32 v44, v36
	v_mul_f32_e32 v36, v38, v54
	v_exp_f32_e32 v45, v36
	v_pk_mul_f32 v[34:35], v[38:39], v[34:35]
	v_add_f32_e32 v38, 1.0, v44
	v_mul_f32_e32 v39, v39, v54
	v_add_f32_e32 v44, 1.0, v45
	v_mul_f32_e32 v45, v47, v54
	v_exp_f32_e32 v45, v45
	v_pk_mul_f32 v[42:43], v[46:47], v[42:43]
	v_exp_f32_e32 v46, v39
	v_rcp_f32_e32 v38, v38
	v_add_f32_e32 v39, 1.0, v45
	v_rcp_f32_e32 v39, v39
	v_add_f32_e32 v45, 1.0, v46
	v_rcp_f32_e32 v44, v44
	v_rcp_f32_e32 v45, v45
	v_pk_mul_f32 v[36:37], v[48:49], v[52:53] op_sel_hi:[0,1]
	v_pk_mul_f32 v[36:37], v[32:33], v[36:37]
	v_pk_mul_f32 v[32:33], v[48:49], v[38:39] op_sel_hi:[0,1]
	v_pk_mul_f32 v[38:39], v[42:43], v[32:33]
	v_pk_mul_f32 v[32:33], v[48:49], v[44:45] op_sel_hi:[0,1]
	v_pk_mul_f32 v[42:43], v[34:35], v[32:33]
	v_cvt_pk_f16_f32 v32, v40, v41
	v_cvt_pk_f16_f32 v33, v38, v39
	v_cvt_pk_f16_f32 v34, v36, v37
	v_cvt_pk_f16_f32 v35, v42, v43
	v_mul_f32_e32 v38, 0xbfb8aa3b, v64
	v_add_co_u32_e32 v210, vcc, 0x16000, v210
	v_addc_co_u32_e32 v211, vcc, 0, v211, vcc
	flat_store_dwordx4 v[210:211], v[32:35]
	v_mul_f32_e32 v36, v29, v38
	v_exp_f32_e32 v37, v36
	v_mul_f32_e32 v35, v20, v38
	v_mul_f32_e32 v32, v28, v38
	v_exp_f32_e32 v35, v35
	v_exp_f32_e32 v34, v32
	v_mul_f32_e32 v39, v21, v38
	v_add_f32_e32 v35, 1.0, v35
	v_add_f32_e32 v34, 1.0, v34
	v_rcp_f32_e32 v36, v35
	v_add_f32_e32 v35, 1.0, v37
	v_rcp_f32_e32 v34, v34
	v_rcp_f32_e32 v35, v35
	v_exp_f32_e32 v37, v39
	v_mul_f32_e32 v32, v64, v64
	v_pk_mul_f32 v[24:25], v[28:29], v[24:25]
	v_pk_mul_f32 v[28:29], v[32:33], v[34:35] op_sel_hi:[0,1]
	v_pk_mul_f32 v[24:25], v[24:25], v[28:29]
	v_add_f32_e32 v28, 1.0, v37
	v_pk_mul_f32 v[16:17], v[20:21], v[16:17]
	v_mul_f32_e32 v20, v30, v38
	v_rcp_f32_e32 v37, v28
	v_exp_f32_e32 v28, v20
	v_mul_f32_e32 v20, v22, v38
	v_exp_f32_e32 v29, v20
	v_pk_mul_f32 v[18:19], v[22:23], v[18:19]
	v_add_f32_e32 v22, 1.0, v28
	v_mul_f32_e32 v23, v23, v38
	v_add_f32_e32 v28, 1.0, v29
	v_mul_f32_e32 v29, v31, v38
	v_exp_f32_e32 v29, v29
	v_pk_mul_f32 v[26:27], v[30:31], v[26:27]
	v_exp_f32_e32 v30, v23
	v_rcp_f32_e32 v22, v22
	v_add_f32_e32 v23, 1.0, v29
	v_rcp_f32_e32 v23, v23
	v_add_f32_e32 v29, 1.0, v30
	v_rcp_f32_e32 v28, v28
	v_rcp_f32_e32 v29, v29
	v_pk_mul_f32 v[20:21], v[32:33], v[36:37] op_sel_hi:[0,1]
	v_pk_mul_f32 v[20:21], v[16:17], v[20:21]
	v_pk_mul_f32 v[16:17], v[32:33], v[22:23] op_sel_hi:[0,1]
	v_pk_mul_f32 v[22:23], v[26:27], v[16:17]
	v_pk_mul_f32 v[16:17], v[32:33], v[28:29] op_sel_hi:[0,1]
	v_pk_mul_f32 v[26:27], v[18:19], v[16:17]
	v_cvt_pk_f16_f32 v16, v24, v25
	v_cvt_pk_f16_f32 v17, v22, v23
	v_cvt_pk_f16_f32 v18, v20, v21
	v_cvt_pk_f16_f32 v19, v26, v27
	v_mul_f32_e32 v22, 0xbfb8aa3b, v65
	v_add_co_u32_e32 v210, vcc, 0x16000, v210
	v_addc_co_u32_e32 v211, vcc, 0, v211, vcc
	flat_store_dwordx4 v[210:211], v[16:19]
	v_mul_f32_e32 v20, v13, v22
	v_exp_f32_e32 v21, v20
	v_mul_f32_e32 v19, v4, v22
	v_mul_f32_e32 v16, v12, v22
	v_exp_f32_e32 v19, v19
	v_exp_f32_e32 v18, v16
	v_mul_f32_e32 v23, v5, v22
	v_add_f32_e32 v19, 1.0, v19
	v_add_f32_e32 v18, 1.0, v18
	v_rcp_f32_e32 v20, v19
	v_add_f32_e32 v19, 1.0, v21
	v_rcp_f32_e32 v18, v18
	v_rcp_f32_e32 v19, v19
	v_exp_f32_e32 v21, v23
	v_mul_f32_e32 v16, v65, v65
	v_pk_mul_f32 v[8:9], v[12:13], v[8:9]
	v_pk_mul_f32 v[12:13], v[16:17], v[18:19] op_sel_hi:[0,1]
	v_pk_mul_f32 v[8:9], v[8:9], v[12:13]
	v_add_f32_e32 v12, 1.0, v21
	v_pk_mul_f32 v[0:1], v[4:5], v[0:1]
	v_mul_f32_e32 v4, v14, v22
	v_rcp_f32_e32 v21, v12
	v_exp_f32_e32 v12, v4
	v_mul_f32_e32 v4, v6, v22
	v_exp_f32_e32 v13, v4
	v_pk_mul_f32 v[2:3], v[6:7], v[2:3]
	v_add_f32_e32 v6, 1.0, v12
	v_mul_f32_e32 v7, v7, v22
	v_add_f32_e32 v12, 1.0, v13
	v_mul_f32_e32 v13, v15, v22
	v_exp_f32_e32 v13, v13
	v_pk_mul_f32 v[10:11], v[14:15], v[10:11]
	v_exp_f32_e32 v14, v7
	v_rcp_f32_e32 v6, v6
	v_add_f32_e32 v7, 1.0, v13
	v_rcp_f32_e32 v7, v7
	v_add_f32_e32 v13, 1.0, v14
	v_rcp_f32_e32 v12, v12
	v_rcp_f32_e32 v13, v13
	v_pk_mul_f32 v[4:5], v[16:17], v[20:21] op_sel_hi:[0,1]
	v_pk_mul_f32 v[4:5], v[0:1], v[4:5]
	v_pk_mul_f32 v[0:1], v[16:17], v[6:7] op_sel_hi:[0,1]
	v_pk_mul_f32 v[6:7], v[10:11], v[0:1]
	v_pk_mul_f32 v[0:1], v[16:17], v[12:13] op_sel_hi:[0,1]
	v_pk_mul_f32 v[10:11], v[2:3], v[0:1]
	v_cvt_pk_f16_f32 v0, v8, v9
	v_cvt_pk_f16_f32 v1, v6, v7
	v_cvt_pk_f16_f32 v2, v4, v5
	v_cvt_pk_f16_f32 v3, v10, v11
	v_add_co_u32_e32 v210, vcc, 0x16000, v210
	v_addc_co_u32_e32 v211, vcc, 0, v211, vcc
	flat_store_dwordx4 v[210:211], v[0:3]
	s_andn2_b64 vcc, exec, s[4:5]
	s_mov_b64 s[4:5], -1
	s_cbranch_vccnz .LBB0_566
	s_andn2_b64 vcc, exec, s[0:1]
	s_cbranch_vccnz .LBB0_565
	s_barrier
	s_branch .LBB0_565
